# speedup vs baseline: 1.0865x; 1.0075x over previous
; DEV f32x4 mfma16(bf16x8 a, bf16x8 b, f32x4 c) { return __builtin_amdgcn_mfma_f32_16x16x32_bf16(a, b, c, 0, 0, 0); }
; template <int EPI, bool AF32>
; DEV void gemm_tile(const void* Ap, int lda, const u16* Bt, int ldb, int K, int m0, int n0, const Epi& ea, char* smem) {
;     ...
;   for (int kt = 0; kt < nk; kt++) {
;     const int buf = kt & 1;
;     if (kt + 1 < nk) swrite(buf ^ 1);
;     if (kt + 2 < nk) gload(kt + 2);
; #pragma unroll
;     for (int ks = 0; ks < 2; ks++) {
;       bf16x8 a[4], b[4];
; #pragma unroll
;       for (int m = 0; m < 4; m++) a[m] = *(const bf16x8*)(sA + buf * 9216 + (wr * 64 + m * 16 + fr) * 72 + ks * 32 + fq * 8);
; #pragma unroll
;       for (int n = 0; n < 4; n++) b[n] = *(const bf16x8*)(sB + buf * 9216 + (wc * 64 + n * 16 + fr) * 72 + ks * 32 + fq * 8);
;       __builtin_amdgcn_s_setprio(1);
; #pragma unroll
;       for (int m = 0; m < 4; m++)
; #pragma unroll
;         for (int n = 0; n < 4; n++) acc[m][n] = mfma16(a[m], b[n], acc[m][n]);
;       __builtin_amdgcn_s_setprio(0);
;     }
;     __syncthreads();
.Lgk1_loop:
	s_waitcnt lgkmcnt(0)
	ds_read_b128 v[222:225], v161 offset:64
	ds_read_b128 v[226:229], v161 offset:2368
	ds_read_b128 v[230:233], v161 offset:4672
	ds_read_b128 v[234:237], v161 offset:6976
	ds_read_b128 v[238:241], v129 offset:36928
	ds_read_b128 v[242:245], v129 offset:39232
	ds_read_b128 v[246:249], v129 offset:41536
	ds_read_b128 v[250:253], v129 offset:43840
	v_mfma_f32_16x16x32_bf16 v[94:97], v[130:133], v[146:149], v[94:97]
	v_mfma_f32_16x16x32_bf16 v[90:93], v[130:133], v[150:153], v[90:93]
	v_mfma_f32_16x16x32_bf16 v[86:89], v[130:133], v[162:165], v[86:89]
	v_mfma_f32_16x16x32_bf16 v[82:85], v[130:133], v[166:169], v[82:85]
	s_waitcnt vmcnt(0)
	ds_write_b128 v122, v[22:25] offset:18432
	ds_write_b128 v122, v[6:9] offset:55296
	v_mfma_f32_16x16x32_bf16 v[78:81], v[134:137], v[146:149], v[78:81]
	ds_write_b128 v121, v[18:21] offset:18432
	ds_write_b128 v121, v[10:13] offset:55296
	v_mfma_f32_16x16x32_bf16 v[74:77], v[134:137], v[150:153], v[74:77]
	ds_write_b128 v120, v[14:17] offset:18432
	ds_write_b128 v120, v[2:5] offset:55296
	v_mfma_f32_16x16x32_bf16 v[70:73], v[134:137], v[162:165], v[70:73]
	ds_write_b128 v124, v[26:29] offset:18432
	ds_write_b128 v124, v[30:33] offset:55296
	v_mfma_f32_16x16x32_bf16 v[66:69], v[134:137], v[166:169], v[66:69]
	global_load_dwordx4 v[22:25], v[112:113], off
	v_mfma_f32_16x16x32_bf16 v[62:65], v[138:141], v[146:149], v[62:65]
	global_load_dwordx4 v[6:9], v[110:111], off
	v_mfma_f32_16x16x32_bf16 v[58:61], v[138:141], v[150:153], v[58:61]
	global_load_dwordx4 v[18:21], v[108:109], off
	v_mfma_f32_16x16x32_bf16 v[54:57], v[138:141], v[162:165], v[54:57]
	global_load_dwordx4 v[10:13], v[106:107], off
	v_mfma_f32_16x16x32_bf16 v[50:53], v[138:141], v[166:169], v[50:53]
	global_load_dwordx4 v[14:17], v[104:105], off
	v_mfma_f32_16x16x32_bf16 v[46:49], v[142:145], v[146:149], v[46:49]
	global_load_dwordx4 v[2:5], v[102:103], off
	v_mfma_f32_16x16x32_bf16 v[42:45], v[142:145], v[150:153], v[42:45]
	global_load_dwordx4 v[26:29], v[100:101], off
	v_mfma_f32_16x16x32_bf16 v[38:41], v[142:145], v[162:165], v[38:41]
	global_load_dwordx4 v[30:33], v[98:99], off
	v_mfma_f32_16x16x32_bf16 v[34:37], v[142:145], v[166:169], v[34:37]
	s_waitcnt lgkmcnt(0)
	s_barrier
	ds_read_b128 v[130:133], v161 offset:18432
	v_mfma_f32_16x16x32_bf16 v[94:97], v[222:225], v[238:241], v[94:97]
	ds_read_b128 v[134:137], v161 offset:20736
	v_mfma_f32_16x16x32_bf16 v[90:93], v[222:225], v[242:245], v[90:93]
	ds_read_b128 v[138:141], v161 offset:23040
	v_mfma_f32_16x16x32_bf16 v[86:89], v[222:225], v[246:249], v[86:89]
	ds_read_b128 v[142:145], v161 offset:25344
	v_mfma_f32_16x16x32_bf16 v[82:85], v[222:225], v[250:253], v[82:85]
	ds_read_b128 v[146:149], v129 offset:55296
	v_mfma_f32_16x16x32_bf16 v[78:81], v[226:229], v[238:241], v[78:81]
	ds_read_b128 v[150:153], v129 offset:57600
	v_mfma_f32_16x16x32_bf16 v[74:77], v[226:229], v[242:245], v[74:77]
	ds_read_b128 v[162:165], v129 offset:59904
	v_mfma_f32_16x16x32_bf16 v[70:73], v[226:229], v[246:249], v[70:73]
	ds_read_b128 v[166:169], v129 offset:62208
	v_mfma_f32_16x16x32_bf16 v[66:69], v[226:229], v[250:253], v[66:69]
	v_mfma_f32_16x16x32_bf16 v[62:65], v[230:233], v[238:241], v[62:65]
	v_mfma_f32_16x16x32_bf16 v[58:61], v[230:233], v[242:245], v[58:61]
	v_mfma_f32_16x16x32_bf16 v[54:57], v[230:233], v[246:249], v[54:57]
	v_mfma_f32_16x16x32_bf16 v[50:53], v[230:233], v[250:253], v[50:53]
	v_mfma_f32_16x16x32_bf16 v[46:49], v[234:237], v[238:241], v[46:49]
	v_mfma_f32_16x16x32_bf16 v[42:45], v[234:237], v[242:245], v[42:45]
	v_mfma_f32_16x16x32_bf16 v[38:41], v[234:237], v[246:249], v[38:41]
	v_mfma_f32_16x16x32_bf16 v[34:37], v[234:237], v[250:253], v[34:37]
	s_waitcnt lgkmcnt(0)
	ds_read_b128 v[222:225], v161 offset:18496
	ds_read_b128 v[226:229], v161 offset:20800
	ds_read_b128 v[230:233], v161 offset:23104
	ds_read_b128 v[234:237], v161 offset:25408
	ds_read_b128 v[238:241], v129 offset:55360
	ds_read_b128 v[242:245], v129 offset:57664
	ds_read_b128 v[246:249], v129 offset:59968
	ds_read_b128 v[250:253], v129 offset:62272
	v_mfma_f32_16x16x32_bf16 v[94:97], v[130:133], v[146:149], v[94:97]
	v_mfma_f32_16x16x32_bf16 v[90:93], v[130:133], v[150:153], v[90:93]
	v_mfma_f32_16x16x32_bf16 v[86:89], v[130:133], v[162:165], v[86:89]
	v_mfma_f32_16x16x32_bf16 v[82:85], v[130:133], v[166:169], v[82:85]
	s_waitcnt vmcnt(0)
	ds_write_b128 v122, v[22:25]
	ds_write_b128 v122, v[6:9] offset:36864
	v_mfma_f32_16x16x32_bf16 v[78:81], v[134:137], v[146:149], v[78:81]
	ds_write_b128 v121, v[18:21]
	ds_write_b128 v121, v[10:13] offset:36864
	v_mfma_f32_16x16x32_bf16 v[74:77], v[134:137], v[150:153], v[74:77]
	ds_write_b128 v120, v[14:17]
	ds_write_b128 v120, v[2:5] offset:36864
	v_mfma_f32_16x16x32_bf16 v[70:73], v[134:137], v[162:165], v[70:73]
	ds_write_b128 v124, v[26:29]
	ds_write_b128 v124, v[30:33] offset:36864
	v_mfma_f32_16x16x32_bf16 v[66:69], v[134:137], v[166:169], v[66:69]
	global_load_dwordx4 v[22:25], v[112:113], off offset:128
	v_mfma_f32_16x16x32_bf16 v[62:65], v[138:141], v[146:149], v[62:65]
	global_load_dwordx4 v[6:9], v[110:111], off offset:128
	v_mfma_f32_16x16x32_bf16 v[58:61], v[138:141], v[150:153], v[58:61]
	global_load_dwordx4 v[18:21], v[108:109], off offset:128
	v_mfma_f32_16x16x32_bf16 v[54:57], v[138:141], v[162:165], v[54:57]
	global_load_dwordx4 v[10:13], v[106:107], off offset:128
	v_mfma_f32_16x16x32_bf16 v[50:53], v[138:141], v[166:169], v[50:53]
	global_load_dwordx4 v[14:17], v[104:105], off offset:128
	v_mfma_f32_16x16x32_bf16 v[46:49], v[142:145], v[146:149], v[46:49]
	global_load_dwordx4 v[2:5], v[102:103], off offset:128
	v_mfma_f32_16x16x32_bf16 v[42:45], v[142:145], v[150:153], v[42:45]
	global_load_dwordx4 v[26:29], v[100:101], off offset:128
	v_mfma_f32_16x16x32_bf16 v[38:41], v[142:145], v[162:165], v[38:41]
	global_load_dwordx4 v[30:33], v[98:99], off offset:128
	v_mfma_f32_16x16x32_bf16 v[34:37], v[142:145], v[166:169], v[34:37]
	s_waitcnt lgkmcnt(0)
	s_barrier
; DEV f32x4 mfma16(bf16x8 a, bf16x8 b, f32x4 c) { return __builtin_amdgcn_mfma_f32_16x16x32_bf16(a, b, c, 0, 0, 0); }
; template <int EPI, bool AF32>
; DEV void gemm_tile(const void* Ap, int lda, const u16* Bt, int ldb, int K, int m0, int n0, const Epi& ea, char* smem) {
;     ...
;   for (int kt = 0; kt < nk; kt++) {
;     const int buf = kt & 1;
;     if (kt + 1 < nk) swrite(buf ^ 1);
;     if (kt + 2 < nk) gload(kt + 2);
; #pragma unroll
;     for (int ks = 0; ks < 2; ks++) {
;       bf16x8 a[4], b[4];
; #pragma unroll
;       for (int m = 0; m < 4; m++) a[m] = *(const bf16x8*)(sA + buf * 9216 + (wr * 64 + m * 16 + fr) * 72 + ks * 32 + fq * 8);
; #pragma unroll
;       for (int n = 0; n < 4; n++) b[n] = *(const bf16x8*)(sB + buf * 9216 + (wc * 64 + n * 16 + fr) * 72 + ks * 32 + fq * 8);
;       __builtin_amdgcn_s_setprio(1);
; #pragma unroll
;       for (int m = 0; m < 4; m++)
; #pragma unroll
;         for (int n = 0; n < 4; n++) acc[m][n] = mfma16(a[m], b[n], acc[m][n]);
;       __builtin_amdgcn_s_setprio(0);
;     }
;     __syncthreads();
	ds_read_b128 v[130:133], v161
	v_mfma_f32_16x16x32_bf16 v[94:97], v[222:225], v[238:241], v[94:97]
	ds_read_b128 v[134:137], v161 offset:2304
	v_mfma_f32_16x16x32_bf16 v[90:93], v[222:225], v[242:245], v[90:93]
	ds_read_b128 v[138:141], v161 offset:4608
	v_mfma_f32_16x16x32_bf16 v[86:89], v[222:225], v[246:249], v[86:89]
	ds_read_b128 v[142:145], v161 offset:6912
	v_mfma_f32_16x16x32_bf16 v[82:85], v[222:225], v[250:253], v[82:85]
	ds_read_b128 v[146:149], v129 offset:36864
	v_mfma_f32_16x16x32_bf16 v[78:81], v[226:229], v[238:241], v[78:81]
	ds_read_b128 v[150:153], v129 offset:39168
	v_mfma_f32_16x16x32_bf16 v[74:77], v[226:229], v[242:245], v[74:77]
	ds_read_b128 v[162:165], v129 offset:41472
	v_mfma_f32_16x16x32_bf16 v[70:73], v[226:229], v[246:249], v[70:73]
	ds_read_b128 v[166:169], v129 offset:43776
	v_mfma_f32_16x16x32_bf16 v[66:69], v[226:229], v[250:253], v[66:69]
	v_mfma_f32_16x16x32_bf16 v[62:65], v[230:233], v[238:241], v[62:65]
	v_lshl_add_u64 v[112:113], v[112:113], 0, s[0:1]
	v_mfma_f32_16x16x32_bf16 v[58:61], v[230:233], v[242:245], v[58:61]
	v_lshl_add_u64 v[110:111], v[110:111], 0, s[0:1]
	v_mfma_f32_16x16x32_bf16 v[54:57], v[230:233], v[246:249], v[54:57]
	v_lshl_add_u64 v[108:109], v[108:109], 0, s[0:1]
	v_mfma_f32_16x16x32_bf16 v[50:53], v[230:233], v[250:253], v[50:53]
	v_lshl_add_u64 v[106:107], v[106:107], 0, s[0:1]
	v_mfma_f32_16x16x32_bf16 v[46:49], v[234:237], v[238:241], v[46:49]
	v_lshl_add_u64 v[104:105], v[104:105], 0, s[0:1]
	v_mfma_f32_16x16x32_bf16 v[42:45], v[234:237], v[242:245], v[42:45]
	v_lshl_add_u64 v[102:103], v[102:103], 0, s[0:1]
	v_mfma_f32_16x16x32_bf16 v[38:41], v[234:237], v[246:249], v[38:41]
	v_lshl_add_u64 v[100:101], v[100:101], 0, s[0:1]
	v_mfma_f32_16x16x32_bf16 v[34:37], v[234:237], v[250:253], v[34:37]
	v_lshl_add_u64 v[98:99], v[98:99], 0, s[0:1]
	s_add_i32 s4, s4, 1
	s_cmp_lg_u32 s4, 7
	s_cbranch_scc1 .Lgk1_loop
	s_waitcnt lgkmcnt(0)
	ds_read_b128 v[222:225], v161 offset:64
	ds_read_b128 v[226:229], v161 offset:2368
	ds_read_b128 v[230:233], v161 offset:4672
	ds_read_b128 v[234:237], v161 offset:6976
	ds_read_b128 v[238:241], v129 offset:36928
	ds_read_b128 v[242:245], v129 offset:39232
	ds_read_b128 v[246:249], v129 offset:41536
	ds_read_b128 v[250:253], v129 offset:43840
	v_mfma_f32_16x16x32_bf16 v[94:97], v[130:133], v[146:149], v[94:97]
	v_mfma_f32_16x16x32_bf16 v[90:93], v[130:133], v[150:153], v[90:93]
	v_mfma_f32_16x16x32_bf16 v[86:89], v[130:133], v[162:165], v[86:89]
	v_mfma_f32_16x16x32_bf16 v[82:85], v[130:133], v[166:169], v[82:85]
	s_waitcnt vmcnt(0)
	ds_write_b128 v122, v[22:25] offset:18432
	ds_write_b128 v122, v[6:9] offset:55296
	v_mfma_f32_16x16x32_bf16 v[78:81], v[134:137], v[146:149], v[78:81]
	ds_write_b128 v121, v[18:21] offset:18432
	ds_write_b128 v121, v[10:13] offset:55296
	v_mfma_f32_16x16x32_bf16 v[74:77], v[134:137], v[150:153], v[74:77]
	ds_write_b128 v120, v[14:17] offset:18432
	ds_write_b128 v120, v[2:5] offset:55296
	v_mfma_f32_16x16x32_bf16 v[70:73], v[134:137], v[162:165], v[70:73]
	ds_write_b128 v124, v[26:29] offset:18432
	ds_write_b128 v124, v[30:33] offset:55296
	v_mfma_f32_16x16x32_bf16 v[66:69], v[134:137], v[166:169], v[66:69]
	v_mfma_f32_16x16x32_bf16 v[62:65], v[138:141], v[146:149], v[62:65]
	v_mfma_f32_16x16x32_bf16 v[58:61], v[138:141], v[150:153], v[58:61]
	v_mfma_f32_16x16x32_bf16 v[54:57], v[138:141], v[162:165], v[54:57]
	v_mfma_f32_16x16x32_bf16 v[50:53], v[138:141], v[166:169], v[50:53]
	v_mfma_f32_16x16x32_bf16 v[46:49], v[142:145], v[146:149], v[46:49]
	v_mfma_f32_16x16x32_bf16 v[42:45], v[142:145], v[150:153], v[42:45]
	v_mfma_f32_16x16x32_bf16 v[38:41], v[142:145], v[162:165], v[38:41]
	v_mfma_f32_16x16x32_bf16 v[34:37], v[142:145], v[166:169], v[34:37]
	s_waitcnt lgkmcnt(0)
	s_barrier
	ds_read_b128 v[130:133], v161 offset:18432
	v_mfma_f32_16x16x32_bf16 v[94:97], v[222:225], v[238:241], v[94:97]
	ds_read_b128 v[134:137], v161 offset:20736
	v_mfma_f32_16x16x32_bf16 v[90:93], v[222:225], v[242:245], v[90:93]
	ds_read_b128 v[138:141], v161 offset:23040
	v_mfma_f32_16x16x32_bf16 v[86:89], v[222:225], v[246:249], v[86:89]
	ds_read_b128 v[142:145], v161 offset:25344
	v_mfma_f32_16x16x32_bf16 v[82:85], v[222:225], v[250:253], v[82:85]
	ds_read_b128 v[146:149], v129 offset:55296
	v_mfma_f32_16x16x32_bf16 v[78:81], v[226:229], v[238:241], v[78:81]
	ds_read_b128 v[150:153], v129 offset:57600
	v_mfma_f32_16x16x32_bf16 v[74:77], v[226:229], v[242:245], v[74:77]
	ds_read_b128 v[162:165], v129 offset:59904
	v_mfma_f32_16x16x32_bf16 v[70:73], v[226:229], v[246:249], v[70:73]
	ds_read_b128 v[166:169], v129 offset:62208
	v_mfma_f32_16x16x32_bf16 v[66:69], v[226:229], v[250:253], v[66:69]
	v_mfma_f32_16x16x32_bf16 v[62:65], v[230:233], v[238:241], v[62:65]
	v_mfma_f32_16x16x32_bf16 v[58:61], v[230:233], v[242:245], v[58:61]
	v_mfma_f32_16x16x32_bf16 v[54:57], v[230:233], v[246:249], v[54:57]
	v_mfma_f32_16x16x32_bf16 v[50:53], v[230:233], v[250:253], v[50:53]
	v_mfma_f32_16x16x32_bf16 v[46:49], v[234:237], v[238:241], v[46:49]
	v_mfma_f32_16x16x32_bf16 v[42:45], v[234:237], v[242:245], v[42:45]
	v_mfma_f32_16x16x32_bf16 v[38:41], v[234:237], v[246:249], v[38:41]
	v_mfma_f32_16x16x32_bf16 v[34:37], v[234:237], v[250:253], v[34:37]
	s_waitcnt lgkmcnt(0)
; DEV f32x4 mfma16(bf16x8 a, bf16x8 b, f32x4 c) { return __builtin_amdgcn_mfma_f32_16x16x32_bf16(a, b, c, 0, 0, 0); }
; template <int EPI, bool AF32>
; DEV void gemm_tile(const void* Ap, int lda, const u16* Bt, int ldb, int K, int m0, int n0, const Epi& ea, char* smem) {
;     ...
;   for (int kt = 0; kt < nk; kt++) {
;     const int buf = kt & 1;
;     if (kt + 1 < nk) swrite(buf ^ 1);
;     if (kt + 2 < nk) gload(kt + 2);
; #pragma unroll
;     for (int ks = 0; ks < 2; ks++) {
;       bf16x8 a[4], b[4];
; #pragma unroll
;       for (int m = 0; m < 4; m++) a[m] = *(const bf16x8*)(sA + buf * 9216 + (wr * 64 + m * 16 + fr) * 72 + ks * 32 + fq * 8);
; #pragma unroll
;       for (int n = 0; n < 4; n++) b[n] = *(const bf16x8*)(sB + buf * 9216 + (wc * 64 + n * 16 + fr) * 72 + ks * 32 + fq * 8);
;       __builtin_amdgcn_s_setprio(1);
; #pragma unroll
;       for (int m = 0; m < 4; m++)
; #pragma unroll
;         for (int n = 0; n < 4; n++) acc[m][n] = mfma16(a[m], b[n], acc[m][n]);
;       __builtin_amdgcn_s_setprio(0);
;     }
;     __syncthreads();
;     ...
;       } else if (EPI == EP_GDNA) {
;         if (cb < 3072) {
;           u16* C = (u16*)ea.p0;
;           u16* H = (u16*)ea.p2;
;           float* O = (float*)ea.p3;
;           const int l = ea.layer;
; #pragma unroll
;           for (int n = 0; n < 4; n++) {
;             const int col = cb + n * 16 + fr;
;             const float v = acc[m][n][j];
;             const u16 hv = f2bf(v);
;             if (row < T_P) {
;               __builtin_nontemporal_store(hv, &C[((size_t)((row >> 6) * 8 + ((col >> 7) & 7)) * 3 + (col >> 10)) * 8192 + (row & 63) * 128 + (col & 127)]);
;               const int r = row & 63, ci = row >> 6;
;               if (r >= 61 && ((ci + 1) & 127) != 0) H[((size_t)(ci + 1) * 3 + (r - 61)) * 3072 + col] = hv;
;               const int pos = row & 8191;
;               if (pos >= 8189) O[O_PCONV + ((size_t)(l * 4 + (row >> 13)) * 3 + (pos - 8189)) * 3072 + col] = v;
	ds_read_b128 v[222:225], v161 offset:18496
	ds_read_b128 v[226:229], v161 offset:20800
	ds_read_b128 v[230:233], v161 offset:23104
	ds_read_b128 v[234:237], v161 offset:25408
	ds_read_b128 v[238:241], v129 offset:55360
	ds_read_b128 v[242:245], v129 offset:57664
	ds_read_b128 v[246:249], v129 offset:59968
	ds_read_b128 v[250:253], v129 offset:62272
	v_mfma_f32_16x16x32_bf16 v[94:97], v[130:133], v[146:149], v[94:97]
	v_mfma_f32_16x16x32_bf16 v[90:93], v[130:133], v[150:153], v[90:93]
	v_mfma_f32_16x16x32_bf16 v[86:89], v[130:133], v[162:165], v[86:89]
	v_mfma_f32_16x16x32_bf16 v[82:85], v[130:133], v[166:169], v[82:85]
	v_mfma_f32_16x16x32_bf16 v[78:81], v[134:137], v[146:149], v[78:81]
	v_mfma_f32_16x16x32_bf16 v[74:77], v[134:137], v[150:153], v[74:77]
	v_mfma_f32_16x16x32_bf16 v[70:73], v[134:137], v[162:165], v[70:73]
	v_mfma_f32_16x16x32_bf16 v[66:69], v[134:137], v[166:169], v[66:69]
	v_mfma_f32_16x16x32_bf16 v[62:65], v[138:141], v[146:149], v[62:65]
	v_mfma_f32_16x16x32_bf16 v[58:61], v[138:141], v[150:153], v[58:61]
	v_mfma_f32_16x16x32_bf16 v[54:57], v[138:141], v[162:165], v[54:57]
	v_mfma_f32_16x16x32_bf16 v[50:53], v[138:141], v[166:169], v[50:53]
	v_mfma_f32_16x16x32_bf16 v[46:49], v[142:145], v[146:149], v[46:49]
	v_mfma_f32_16x16x32_bf16 v[42:45], v[142:145], v[150:153], v[42:45]
	v_mfma_f32_16x16x32_bf16 v[38:41], v[142:145], v[162:165], v[38:41]
	v_mfma_f32_16x16x32_bf16 v[34:37], v[142:145], v[166:169], v[34:37]
	s_waitcnt lgkmcnt(0)
	v_mfma_f32_16x16x32_bf16 v[30:33], v[230:233], v[238:241], v[62:65]
	v_mfma_f32_16x16x32_bf16 v[26:29], v[230:233], v[242:245], v[58:61]
	v_mfma_f32_16x16x32_bf16 v[22:25], v[230:233], v[246:249], v[54:57]
	v_mfma_f32_16x16x32_bf16 v[18:21], v[230:233], v[250:253], v[50:53]
	v_mfma_f32_16x16x32_bf16 v[14:17], v[234:237], v[238:241], v[46:49]
	v_mfma_f32_16x16x32_bf16 v[10:13], v[234:237], v[242:245], v[42:45]
	v_mfma_f32_16x16x32_bf16 v[6:9], v[234:237], v[246:249], v[38:41]
	v_mfma_f32_16x16x32_bf16 v[2:5], v[234:237], v[250:253], v[34:37]
	v_mfma_f32_16x16x32_bf16 v[62:65], v[222:225], v[238:241], v[94:97]
	v_mfma_f32_16x16x32_bf16 v[58:61], v[222:225], v[242:245], v[90:93]
	v_mfma_f32_16x16x32_bf16 v[54:57], v[222:225], v[246:249], v[86:89]
	v_mfma_f32_16x16x32_bf16 v[50:53], v[222:225], v[250:253], v[82:85]
	v_mfma_f32_16x16x32_bf16 v[46:49], v[226:229], v[238:241], v[78:81]
	v_mfma_f32_16x16x32_bf16 v[42:45], v[226:229], v[242:245], v[74:77]
	v_mfma_f32_16x16x32_bf16 v[38:41], v[226:229], v[246:249], v[70:73]
	v_mfma_f32_16x16x32_bf16 v[34:37], v[226:229], v[250:253], v[66:69]
	s_nop 7
	s_cmp_lt_u32 s2, 0x8000
	s_cbranch_scc0 .Lgd_orig
	s_cmpk_lt_u32 s3, 0xc00
	s_cbranch_scc0 .Lgd_orig
	v_and_b32_e32 v66, 15, v157
	v_bfe_u32 v67, v157, 4, 2
	v_bfe_u32 v68, v157, 6, 1
	v_lshrrev_b32_e32 v69, 7, v157
	s_nop 0
	v_readfirstlane_b32 s4, v69
	s_lshr_b32 s5, s2, 6
	s_add_i32 s5, s5, s4
	s_and_b32 s6, s29, 7
	s_lshr_b32 s7, s29, 3
	s_lshl_b32 s8, s5, 3
	s_add_i32 s8, s8, s6
	s_mul_i32 s8, s8, 3
	s_add_i32 s8, s8, s7
	s_lshl_b32 s8, s8, 14
	s_add_u32 s10, s62, s8
	s_addc_u32 s11, s63, 0
	s_add_u32 s10, s10, 0x2800000
	s_addc_u32 s11, s11, 0
	v_lshlrev_b32_e32 v70, 10, v67
	v_lshl_add_u32 v70, v68, 7, v70
	v_lshl_add_u32 v70, v66, 1, v70
	v_mov_b32_e32 v71, 0
	v_lshl_add_u64 v[70:71], s[10:11], 0, v[70:71]
	s_mov_b64 s[8:9], 0x1000
	s_barrier
	v_cvt_pk_bf16_f32 v72, v62, v62
	global_store_short v[70:71], v72, off nt
	v_cvt_pk_bf16_f32 v73, v58, v58
	global_store_short v[70:71], v73, off offset:32 nt
	v_cvt_pk_bf16_f32 v74, v54, v54
	global_store_short v[70:71], v74, off offset:64 nt
	v_cvt_pk_bf16_f32 v75, v50, v50
	global_store_short v[70:71], v75, off offset:96 nt
	v_cvt_pk_bf16_f32 v72, v63, v63
	global_store_short v[70:71], v72, off offset:256 nt
	v_cvt_pk_bf16_f32 v73, v59, v59
	global_store_short v[70:71], v73, off offset:288 nt
	v_cvt_pk_bf16_f32 v74, v55, v55
	global_store_short v[70:71], v74, off offset:320 nt
	v_cvt_pk_bf16_f32 v75, v51, v51
	global_store_short v[70:71], v75, off offset:352 nt
	v_cvt_pk_bf16_f32 v72, v64, v64
	global_store_short v[70:71], v72, off offset:512 nt
	v_cvt_pk_bf16_f32 v73, v60, v60
	global_store_short v[70:71], v73, off offset:544 nt
	v_cvt_pk_bf16_f32 v74, v56, v56
	global_store_short v[70:71], v74, off offset:576 nt
	v_cvt_pk_bf16_f32 v75, v52, v52
	global_store_short v[70:71], v75, off offset:608 nt
	v_cvt_pk_bf16_f32 v72, v65, v65
	global_store_short v[70:71], v72, off offset:768 nt
	v_cvt_pk_bf16_f32 v73, v61, v61
	global_store_short v[70:71], v73, off offset:800 nt
	v_cvt_pk_bf16_f32 v74, v57, v57
	global_store_short v[70:71], v74, off offset:832 nt
	v_cvt_pk_bf16_f32 v75, v53, v53
	global_store_short v[70:71], v75, off offset:864 nt
	v_lshl_add_u64 v[70:71], v[70:71], 0, s[8:9]
	v_cvt_pk_bf16_f32 v72, v46, v46
	global_store_short v[70:71], v72, off nt
	v_cvt_pk_bf16_f32 v73, v42, v42
	global_store_short v[70:71], v73, off offset:32 nt
	v_cvt_pk_bf16_f32 v74, v38, v38
	global_store_short v[70:71], v74, off offset:64 nt
	v_cvt_pk_bf16_f32 v75, v34, v34
	global_store_short v[70:71], v75, off offset:96 nt
	v_cvt_pk_bf16_f32 v72, v47, v47
	global_store_short v[70:71], v72, off offset:256 nt
	v_cvt_pk_bf16_f32 v73, v43, v43
	global_store_short v[70:71], v73, off offset:288 nt
	v_cvt_pk_bf16_f32 v74, v39, v39
	global_store_short v[70:71], v74, off offset:320 nt
	v_cvt_pk_bf16_f32 v75, v35, v35
	global_store_short v[70:71], v75, off offset:352 nt
	v_cvt_pk_bf16_f32 v72, v48, v48
	global_store_short v[70:71], v72, off offset:512 nt
	v_cvt_pk_bf16_f32 v73, v44, v44
	global_store_short v[70:71], v73, off offset:544 nt
	v_cvt_pk_bf16_f32 v74, v40, v40
; template <int EPI, bool AF32>
; DEV void gemm_tile(const void* Ap, int lda, const u16* Bt, int ldb, int K, int m0, int n0, const Epi& ea, char* smem) {
;     ...
;       } else if (EPI == EP_GDNA) {
;         if (cb < 3072) {
;           u16* C = (u16*)ea.p0;
;           u16* H = (u16*)ea.p2;
;           float* O = (float*)ea.p3;
;           const int l = ea.layer;
; #pragma unroll
;           for (int n = 0; n < 4; n++) {
;             const int col = cb + n * 16 + fr;
;             const float v = acc[m][n][j];
;             const u16 hv = f2bf(v);
;             if (row < T_P) {
;               __builtin_nontemporal_store(hv, &C[((size_t)((row >> 6) * 8 + ((col >> 7) & 7)) * 3 + (col >> 10)) * 8192 + (row & 63) * 128 + (col & 127)]);
;               const int r = row & 63, ci = row >> 6;
;               if (r >= 61 && ((ci + 1) & 127) != 0) H[((size_t)(ci + 1) * 3 + (r - 61)) * 3072 + col] = hv;
;               const int pos = row & 8191;
;               if (pos >= 8189) O[O_PCONV + ((size_t)(l * 4 + (row >> 13)) * 3 + (pos - 8189)) * 3072 + col] = v;
;             } else {
;               const int ts = row - T_P, i = ts & 31;
;               ((u16*)ea.p2)[(size_t)(56590336 / 2) + (size_t)ts * 3072 + col] = hv;
;               if (i >= 29) O[O_SCONV + ((size_t)(l * 16 + (ts >> 5)) * 3 + (i - 29)) * 3072 + col] = v;
;             }
;           }
;         } else {
;           u16* Z = (u16*)ea.p1;
; #pragma unroll
;           for (int n = 0; n < 4; n++) Z[(size_t)row * 1024 + cb - 3072 + n * 16 + fr] = f2bf(acc[m][n][j]);
	global_store_short v[70:71], v74, off offset:576 nt
	v_cvt_pk_bf16_f32 v75, v36, v36
	global_store_short v[70:71], v75, off offset:608 nt
	v_cvt_pk_bf16_f32 v72, v49, v49
	global_store_short v[70:71], v72, off offset:768 nt
	v_cvt_pk_bf16_f32 v73, v45, v45
	global_store_short v[70:71], v73, off offset:800 nt
	v_cvt_pk_bf16_f32 v74, v41, v41
	global_store_short v[70:71], v74, off offset:832 nt
	v_cvt_pk_bf16_f32 v75, v37, v37
	global_store_short v[70:71], v75, off offset:864 nt
	v_lshl_add_u64 v[70:71], v[70:71], 0, s[8:9]
	v_cvt_pk_bf16_f32 v72, v30, v30
	global_store_short v[70:71], v72, off nt
	v_cvt_pk_bf16_f32 v73, v26, v26
	global_store_short v[70:71], v73, off offset:32 nt
	v_cvt_pk_bf16_f32 v74, v22, v22
	global_store_short v[70:71], v74, off offset:64 nt
	v_cvt_pk_bf16_f32 v75, v18, v18
	global_store_short v[70:71], v75, off offset:96 nt
	v_cvt_pk_bf16_f32 v72, v31, v31
	global_store_short v[70:71], v72, off offset:256 nt
	v_cvt_pk_bf16_f32 v73, v27, v27
	global_store_short v[70:71], v73, off offset:288 nt
	v_cvt_pk_bf16_f32 v74, v23, v23
	global_store_short v[70:71], v74, off offset:320 nt
	v_cvt_pk_bf16_f32 v75, v19, v19
	global_store_short v[70:71], v75, off offset:352 nt
	v_cvt_pk_bf16_f32 v72, v32, v32
	global_store_short v[70:71], v72, off offset:512 nt
	v_cvt_pk_bf16_f32 v73, v28, v28
	global_store_short v[70:71], v73, off offset:544 nt
	v_cvt_pk_bf16_f32 v74, v24, v24
	global_store_short v[70:71], v74, off offset:576 nt
	v_cvt_pk_bf16_f32 v75, v20, v20
	global_store_short v[70:71], v75, off offset:608 nt
	v_cvt_pk_bf16_f32 v72, v33, v33
	global_store_short v[70:71], v72, off offset:768 nt
	v_cvt_pk_bf16_f32 v73, v29, v29
	global_store_short v[70:71], v73, off offset:800 nt
	v_cvt_pk_bf16_f32 v74, v25, v25
	global_store_short v[70:71], v74, off offset:832 nt
	v_cvt_pk_bf16_f32 v75, v21, v21
	global_store_short v[70:71], v75, off offset:864 nt
	v_lshl_add_u64 v[70:71], v[70:71], 0, s[8:9]
	v_cvt_pk_bf16_f32 v72, v14, v14
	global_store_short v[70:71], v72, off nt
	v_cvt_pk_bf16_f32 v73, v10, v10
	global_store_short v[70:71], v73, off offset:32 nt
	v_cvt_pk_bf16_f32 v74, v6, v6
	global_store_short v[70:71], v74, off offset:64 nt
	v_cvt_pk_bf16_f32 v75, v2, v2
	global_store_short v[70:71], v75, off offset:96 nt
	v_cvt_pk_bf16_f32 v72, v15, v15
	global_store_short v[70:71], v72, off offset:256 nt
	v_cvt_pk_bf16_f32 v73, v11, v11
	global_store_short v[70:71], v73, off offset:288 nt
	v_cvt_pk_bf16_f32 v74, v7, v7
	global_store_short v[70:71], v74, off offset:320 nt
	v_cvt_pk_bf16_f32 v75, v3, v3
	global_store_short v[70:71], v75, off offset:352 nt
	v_cvt_pk_bf16_f32 v72, v16, v16
	global_store_short v[70:71], v72, off offset:512 nt
	v_cvt_pk_bf16_f32 v73, v12, v12
	global_store_short v[70:71], v73, off offset:544 nt
	v_cvt_pk_bf16_f32 v74, v8, v8
	global_store_short v[70:71], v74, off offset:576 nt
	v_cvt_pk_bf16_f32 v75, v4, v4
	global_store_short v[70:71], v75, off offset:608 nt
	v_cvt_pk_bf16_f32 v72, v17, v17
	global_store_short v[70:71], v72, off offset:768 nt
	v_cvt_pk_bf16_f32 v73, v13, v13
	global_store_short v[70:71], v73, off offset:800 nt
	v_cvt_pk_bf16_f32 v74, v9, v9
	global_store_short v[70:71], v74, off offset:832 nt
	v_cvt_pk_bf16_f32 v75, v5, v5
	global_store_short v[70:71], v75, off offset:864 nt
	v_cmp_eq_u32_e32 vcc, 3, v67
	s_and_saveexec_b64 s[6:7], vcc
	s_cbranch_execz .Lgd_done
	v_lshl_add_u32 v72, v68, 6, v66
	v_add_u32_e32 v72, s3, v72
	v_mov_b32_e32 v73, 0
	s_and_b32 s8, s5, 0x7f
	s_cmp_eq_u32 s8, 0x7f
	s_cbranch_scc1 .Lgd_pconv
	s_add_i32 s8, s5, 1
	s_mul_i32 s8, s8, 0x4800
	s_add_u32 s10, s62, s8
	s_addc_u32 s11, s63, 0
	s_add_u32 s10, s10, 0x1b008000
	s_addc_u32 s11, s11, 0
	v_lshlrev_b32_e32 v72, 1, v72
	v_lshl_add_u64 v[72:73], s[10:11], 0, v[72:73]
	s_mov_b64 s[8:9], 0x1800
	v_cvt_pk_bf16_f32 v74, v15, v15
	global_store_short v[72:73], v74, off
	v_cvt_pk_bf16_f32 v75, v11, v11
	global_store_short v[72:73], v75, off offset:32
	v_cvt_pk_bf16_f32 v74, v7, v7
	global_store_short v[72:73], v74, off offset:64
	v_cvt_pk_bf16_f32 v75, v3, v3
	global_store_short v[72:73], v75, off offset:96
	v_lshl_add_u64 v[72:73], v[72:73], 0, s[8:9]
	v_cvt_pk_bf16_f32 v74, v16, v16
	global_store_short v[72:73], v74, off
	v_cvt_pk_bf16_f32 v75, v12, v12
	global_store_short v[72:73], v75, off offset:32
	v_cvt_pk_bf16_f32 v74, v8, v8
	global_store_short v[72:73], v74, off offset:64
	v_cvt_pk_bf16_f32 v75, v4, v4
	global_store_short v[72:73], v75, off offset:96
	v_lshl_add_u64 v[72:73], v[72:73], 0, s[8:9]
	v_cvt_pk_bf16_f32 v74, v17, v17
	global_store_short v[72:73], v74, off
	v_cvt_pk_bf16_f32 v75, v13, v13
	global_store_short v[72:73], v75, off offset:32
	v_cvt_pk_bf16_f32 v74, v9, v9
	global_store_short v[72:73], v74, off offset:64
	v_cvt_pk_bf16_f32 v75, v5, v5
	global_store_short v[72:73], v75, off offset:96
	s_branch .Lgd_done
.Lgd_pconv:
	s_lshr_b32 s8, s2, 13
	s_add_i32 s8, s8, s28
	s_mul_i32 s8, s8, 0x9000
	s_add_u32 s10, s60, s8
	s_addc_u32 s11, s61, 0
	s_add_u32 s10, s10, 0x8200000
	s_addc_u32 s11, s11, 0
	v_lshlrev_b32_e32 v72, 2, v72
	v_lshl_add_u64 v[72:73], s[10:11], 0, v[72:73]
	s_mov_b64 s[8:9], 0x3000
	global_store_dword v[72:73], v15, off
	global_store_dword v[72:73], v11, off offset:64
	global_store_dword v[72:73], v7, off offset:128
	global_store_dword v[72:73], v3, off offset:192
	v_lshl_add_u64 v[72:73], v[72:73], 0, s[8:9]
	global_store_dword v[72:73], v16, off
	global_store_dword v[72:73], v12, off offset:64
	global_store_dword v[72:73], v8, off offset:128
	global_store_dword v[72:73], v4, off offset:192
	v_lshl_add_u64 v[72:73], v[72:73], 0, s[8:9]
	global_store_dword v[72:73], v17, off
	global_store_dword v[72:73], v13, off offset:64
	global_store_dword v[72:73], v9, off offset:128
	global_store_dword v[72:73], v5, off offset:192
.Lgd_done:
	s_or_b64 exec, exec, s[6:7]
	s_branch .LBB0_546
.Lgd_orig:
	v_and_or_b32 v0, v114, 64, s3
	v_add_u32_e32 v80, s2, v117
	s_movk_i32 s0, 0xbff
	v_lshl_or_b32 v68, v115, 2, v80
	v_cmp_lt_i32_e64 s[2:3], s0, v0
	v_lshl_add_u64 v[72:73], v[0:1], 1, s[16:17]
	v_lshlrev_b32_e32 v70, 1, v116
	s_barrier
	s_and_saveexec_b64 s[0:1], s[2:3]
	s_xor_b64 s[0:1], exec, s[0:1]
	s_cbranch_execz .LBB0_551
	v_ashrrev_i32_e32 v69, 31, v68
	v_lshlrev_b64 v[66:67], 11, v[68:69]
	v_lshl_add_u64 v[66:67], v[72:73], 0, v[66:67]
	v_mov_b32_e32 v71, v1
	v_lshl_add_u64 v[66:67], v[66:67], 0, v[70:71]
	v_lshl_add_u64 v[74:75], v[66:67], 0, s[36:37]
	v_add_co_u32_e32 v66, vcc, 0xfffff000, v66
	v_cvt_pk_bf16_f32 v69, v62, s0
	s_nop 0
	v_addc_co_u32_e32 v67, vcc, -1, v67, vcc
	global_store_short v[66:67], v69, off offset:-2048
	v_cvt_pk_bf16_f32 v66, v58, s0
	global_store_short v[74:75], v66, off offset:32
	v_cvt_pk_bf16_f32 v66, v54, s0
	global_store_short v[74:75], v66, off offset:64
	v_cvt_pk_bf16_f32 v66, v50, s0
	global_store_short v[74:75], v66, off offset:96
